# v_c14 + the two running-max canonicalizes folded into the max (v_max m_run,m_run then max -> one v_max)
# speedup vs baseline: 1.0032x; 1.0032x over previous
; __device__ __forceinline__ float xor16_max(float v) { const auto r = __builtin_amdgcn_permlane16_swap(__float_as_uint(v), __float_as_uint(v), false, false); return fmaxf(__uint_as_float(r[0]), __uint_as_float(r[1])); }
; __device__ __forceinline__ void attn_phase(LAS unsigned char* lds, const bf16* PROJ, bf16* MIX, const float* lq1, const float* lk1, const float* lq2, const float* lk2,
;                                            const float* norm_g, float lambda_init, int G, int wave_s) {
;     ...
;                 { bf16x8 kfa[4], kfb[4];
;                   ATT_LDK(kfa, 0); ATT_LDK(kfb, 1); ATT_SB(); ATT_QK(kfa, 0); ATT_LDK(kfa, 2); ATT_SB(); ATT_QK(kfb, 1); ATT_LDK(kfb, 3); ATT_SB(); ATT_QK(kfa, 2); ATT_QK(kfb, 3); }
;                 const int dq = 64 * kt + qloc; const bool diag = (kt == 0);
;                 const float nb = -sl2 * ((float)dq - q4f);
;                 float mx = -1e30f;
; #pragma unroll
;                 for (int t16 = 0; t16 < 4; ++t16)
; #pragma unroll
;                     for (int r = 0; r < 4; ++r) { const int kl = 16 * t16 + 4 * q4 + r; float v = fmaf(s[t16][r], c1, fmaf(sl2, (float)(16 * t16 + r), nb));
;                         if (diag && kl > qloc) v = -1e30f; s[t16][r] = v; mx = fmaxf(mx, v); }
;                 mx = xor32_max(xor16_max(mx));
;                 const bool resc = __builtin_amdgcn_ballot_w64(mx > m_run) != 0ull;
;                 const float mn = fmaxf(m_run, mx), alpha = __builtin_amdgcn_exp2f(m_run - mn); m_run = mn;
;                 float ps = 0.f;
; #pragma unroll
;                 for (int t16 = 0; t16 < 4; ++t16)
; #pragma unroll
;                     for (int r = 0; r < 4; ++r) { const float pv = __builtin_amdgcn_exp2f(s[t16][r] - mn); s[t16][r] = pv; ps += pv; }
;                 l_part = l_part * alpha + ps;
;                 bf16x8 pf[2];
; #pragma unroll
;                 for (int ks = 0; ks < 2; ++ks) { v4u pw; pw.x = pk2(s[2 * ks][0], s[2 * ks][1]); pw.y = pk2(s[2 * ks][2], s[2 * ks][3]); pw.z = pk2(s[2 * ks + 1][0], s[2 * ks + 1][1]); pw.w = pk2(s[2 * ks + 1][2], s[2 * ks + 1][3]);
;                     pf[ks] = __builtin_bit_cast(bf16x8, pw); }
;                 { bf16x8 va[2], vb[2], vc[2];
;                   ATT_LDV(va, 0); ATT_LDV(vb, 1);
;                   if (resc) {
; #pragma unroll
;                   for (int mt = 0; mt < 16; ++mt) O[mt] = O[mt] * alpha; }
.LBB0_892:
	ds_read_b128 v[114:117], v209
	ds_read_b128 v[118:121], v209 offset:64
	ds_read_b128 v[122:125], v209 offset:128
	ds_read_b128 v[126:129], v209 offset:192
	ds_read_b128 v[130:133], v209 offset:4352
	ds_read_b128 v[134:137], v209 offset:4416
	ds_read_b128 v[228:231], v209 offset:4480
	ds_read_b128 v[232:235], v209 offset:4544
	s_waitcnt lgkmcnt(7)
	v_mfma_f32_16x16x32_bf16 v[114:117], v[114:117], v[74:77], 0
	s_waitcnt lgkmcnt(6)
	v_mfma_f32_16x16x32_bf16 v[114:117], v[118:121], v[66:69], v[114:117]
	s_waitcnt lgkmcnt(5)
	v_mfma_f32_16x16x32_bf16 v[114:117], v[122:125], v[70:73], v[114:117]
	s_waitcnt lgkmcnt(4)
	v_mfma_f32_16x16x32_bf16 v[114:117], v[126:129], v[78:81], v[114:117]
	ds_read_b128 v[118:121], v209 offset:8704
	ds_read_b128 v[122:125], v209 offset:8768
	ds_read_b128 v[126:129], v209 offset:8832
	ds_read_b128 v[236:239], v209 offset:8896
	s_waitcnt lgkmcnt(7)
	v_mfma_f32_16x16x32_bf16 v[130:133], v[130:133], v[74:77], 0
	s_waitcnt lgkmcnt(6)
	v_mfma_f32_16x16x32_bf16 v[130:133], v[134:137], v[66:69], v[130:133]
	s_waitcnt lgkmcnt(5)
	v_mfma_f32_16x16x32_bf16 v[130:133], v[228:231], v[70:73], v[130:133]
	s_waitcnt lgkmcnt(4)
	v_mfma_f32_16x16x32_bf16 v[134:137], v[232:235], v[78:81], v[130:133]
	s_nop 5
	ds_read_b128 v[130:133], v209 offset:13056
	ds_read_b128 v[228:231], v209 offset:13120
	ds_read_b128 v[232:235], v209 offset:13184
	ds_read_b128 v[240:243], v209 offset:13248
	s_waitcnt lgkmcnt(7)
	v_mfma_f32_16x16x32_bf16 v[118:121], v[118:121], v[74:77], 0
	v_cvt_f32_u32_e32 v0, v224
	s_cmp_eq_u32 s88, 0
	s_cselect_b64 s[26:27], -1, 0
	s_waitcnt lgkmcnt(6)
	v_mfma_f32_16x16x32_bf16 v[118:121], v[122:125], v[66:69], v[118:121]
	v_sub_f32_e32 v0, v0, v166
	s_and_b64 vcc, s[26:27], s[40:41]
	s_waitcnt lgkmcnt(5)
	v_mfma_f32_16x16x32_bf16 v[118:121], v[126:129], v[70:73], v[118:121]
	v_mul_f32_e64 v126, v0, -v211
	v_fma_f32 v127, 0, v211, v126
	v_fmac_f32_e32 v127, 0x3e0293ee, v114
	v_fma_f32 v0, v0, -v211, v211
	s_waitcnt lgkmcnt(3)
	v_mfma_f32_16x16x32_bf16 v[122:125], v[130:133], v[74:77], 0
	v_cndmask_b32_e32 v130, v127, v219, vcc
	v_fmac_f32_e32 v0, 0x3e0293ee, v115
	s_and_b64 vcc, s[26:27], s[42:43]
	v_fma_f32 v114, 2.0, v211, v126
	v_cndmask_b32_e32 v131, v0, v219, vcc
	v_fmac_f32_e32 v114, 0x3e0293ee, v116
	s_and_b64 vcc, s[26:27], s[44:45]
	v_cndmask_b32_e32 v132, v114, v219, vcc
	v_fmamk_f32 v114, v211, 0x40400000, v126
	v_fmac_f32_e32 v114, 0x3e0293ee, v117
	s_and_b64 vcc, s[26:27], s[46:47]
	v_cndmask_b32_e32 v133, v114, v219, vcc
	v_fmamk_f32 v114, v211, 0x41800000, v126
	v_fmac_f32_e32 v114, 0x3e0293ee, v134
	s_and_b64 vcc, s[26:27], s[48:49]
	v_cndmask_b32_e32 v134, v114, v219, vcc
	v_fmamk_f32 v114, v211, 0x41880000, v126
	v_fmac_f32_e32 v114, 0x3e0293ee, v135
	s_and_b64 vcc, s[26:27], s[50:51]
	v_cndmask_b32_e32 v135, v114, v219, vcc
	v_fmamk_f32 v114, v211, 0x41900000, v126
	v_mfma_f32_16x16x32_bf16 v[118:121], v[236:239], v[78:81], v[118:121]
	v_fmac_f32_e32 v114, 0x3e0293ee, v136
	s_and_b64 vcc, s[26:27], s[52:53]
	v_cndmask_b32_e32 v136, v114, v219, vcc
	s_waitcnt lgkmcnt(2)
	v_mfma_f32_16x16x32_bf16 v[122:125], v[228:231], v[66:69], v[122:125]
	v_fmamk_f32 v114, v211, 0x41980000, v126
	v_fmac_f32_e32 v114, 0x3e0293ee, v137
	s_and_b64 vcc, s[26:27], s[54:55]
	v_cndmask_b32_e32 v137, v114, v219, vcc
	v_fmamk_f32 v114, v211, 0x42000000, v126
	s_waitcnt lgkmcnt(1)
	v_mfma_f32_16x16x32_bf16 v[122:125], v[232:235], v[70:73], v[122:125]
	v_fmac_f32_e32 v114, 0x3e0293ee, v118
	s_and_b64 vcc, s[26:27], s[56:57]
	v_cndmask_b32_e32 v227, v114, v219, vcc
	v_fmamk_f32 v114, v211, 0x42040000, v126
	v_fmac_f32_e32 v114, 0x3e0293ee, v119
	s_and_b64 vcc, s[26:27], s[58:59]
	v_cndmask_b32_e32 v229, v114, v219, vcc
	v_fmamk_f32 v114, v211, 0x42080000, v126
	s_waitcnt lgkmcnt(0)
	v_mfma_f32_16x16x32_bf16 v[122:125], v[240:243], v[78:81], v[122:125]
	v_fmac_f32_e32 v114, 0x3e0293ee, v120
	s_and_b64 vcc, s[26:27], s[60:61]
	v_cndmask_b32_e32 v230, v114, v219, vcc
	v_fmamk_f32 v114, v211, 0x420c0000, v126
	v_fmac_f32_e32 v114, 0x3e0293ee, v121
	s_and_b64 vcc, s[26:27], s[62:63]
	v_cndmask_b32_e32 v231, v114, v219, vcc
	v_fmamk_f32 v114, v211, 0x42400000, v126
	v_max3_f32 v0, v130, s4, v131
	v_fmac_f32_e32 v114, 0x3e0293ee, v122
	s_and_b64 vcc, s[26:27], s[64:65]
	v_max3_f32 v0, v0, v132, v133
	v_cndmask_b32_e32 v232, v114, v219, vcc
	v_fmamk_f32 v114, v211, 0x42440000, v126
	v_max3_f32 v0, v0, v134, v135
	v_fmac_f32_e32 v114, 0x3e0293ee, v123
	s_and_b64 vcc, s[26:27], s[66:67]
	v_max3_f32 v0, v0, v136, v137
	v_cndmask_b32_e32 v233, v114, v219, vcc
	v_fmamk_f32 v114, v211, 0x42480000, v126
	v_max3_f32 v0, v0, v227, v229
	v_fmac_f32_e32 v114, 0x3e0293ee, v124
	s_and_b64 vcc, s[26:27], s[68:69]
	v_fmac_f32_e32 v126, 0x424c0000, v211
	v_max3_f32 v0, v0, v230, v231
	v_cndmask_b32_e32 v234, v114, v219, vcc
	v_fmac_f32_e32 v126, 0x3e0293ee, v125
	s_and_b64 vcc, s[26:27], s[70:71]
	v_max3_f32 v0, v0, v232, v233
	v_cndmask_b32_e32 v235, v126, v219, vcc
	v_max3_f32 v0, v0, v234, v235
	v_mov_b32_e32 v114, v0
	s_nop 1
	v_permlane16_swap_b32_e32 v0, v114
	v_max_f32_e32 v0, v0, v114
	v_mov_b32_e32 v114, v0
	s_nop 1
	v_permlane32_swap_b32_e32 v0, v114
	v_max_f32_e32 v0, v0, v114
	v_max_f32_e32 v228, v226, v0
	ds_read_b64_tr_b16 v[126:127], v162 offset:34816
	ds_read_b64_tr_b16 v[114:115], v162 offset:34848
	ds_read_b64_tr_b16 v[128:129], v162 offset:43520
	ds_read_b64_tr_b16 v[122:123], v162 offset:52224
	ds_read_b64_tr_b16 v[124:125], v162 offset:60928
	ds_read_b64_tr_b16 v[116:117], v162 offset:43552
	ds_read_b64_tr_b16 v[118:119], v162 offset:52256
	ds_read_b64_tr_b16 v[120:121], v162 offset:60960
	v_cmp_gt_f32_e32 vcc, v0, v226
	v_sub_f32_e32 v0, v226, v228
	v_exp_f32_e32 v0, v0
	s_cbranch_vccz .LBB0_894
; __device__ __forceinline__ void attn_phase(LAS unsigned char* lds, const bf16* PROJ, bf16* MIX, const float* lq1, const float* lk1, const float* lq2, const float* lk2,
;                                            const float* norm_g, float lambda_init, int G, int wave_s) {
;     ...
;                   if (resc) {
; #pragma unroll
;                   for (int mt = 0; mt < 16; ++mt) O[mt] = O[mt] * alpha; }
	v_pk_mul_f32 v[64:65], v[64:65], v[0:1] op_sel_hi:[1,0]
	v_pk_mul_f32 v[62:63], v[62:63], v[0:1] op_sel_hi:[1,0]
	v_pk_mul_f32 v[60:61], v[60:61], v[0:1] op_sel_hi:[1,0]
	v_pk_mul_f32 v[58:59], v[58:59], v[0:1] op_sel_hi:[1,0]
	v_pk_mul_f32 v[56:57], v[56:57], v[0:1] op_sel_hi:[1,0]
	v_pk_mul_f32 v[54:55], v[54:55], v[0:1] op_sel_hi:[1,0]
	v_pk_mul_f32 v[52:53], v[52:53], v[0:1] op_sel_hi:[1,0]
	v_pk_mul_f32 v[50:51], v[50:51], v[0:1] op_sel_hi:[1,0]
	v_pk_mul_f32 v[48:49], v[48:49], v[0:1] op_sel_hi:[1,0]
	v_pk_mul_f32 v[46:47], v[46:47], v[0:1] op_sel_hi:[1,0]
	v_pk_mul_f32 v[44:45], v[44:45], v[0:1] op_sel_hi:[1,0]
	v_pk_mul_f32 v[42:43], v[42:43], v[0:1] op_sel_hi:[1,0]
	v_pk_mul_f32 v[40:41], v[40:41], v[0:1] op_sel_hi:[1,0]
	v_pk_mul_f32 v[38:39], v[38:39], v[0:1] op_sel_hi:[1,0]
	v_pk_mul_f32 v[36:37], v[36:37], v[0:1] op_sel_hi:[1,0]
	v_pk_mul_f32 v[34:35], v[34:35], v[0:1] op_sel_hi:[1,0]
	v_pk_mul_f32 v[32:33], v[32:33], v[0:1] op_sel_hi:[1,0]
	v_pk_mul_f32 v[30:31], v[30:31], v[0:1] op_sel_hi:[1,0]
	v_pk_mul_f32 v[28:29], v[28:29], v[0:1] op_sel_hi:[1,0]
	v_pk_mul_f32 v[26:27], v[26:27], v[0:1] op_sel_hi:[1,0]
	v_pk_mul_f32 v[24:25], v[24:25], v[0:1] op_sel_hi:[1,0]
	v_pk_mul_f32 v[22:23], v[22:23], v[0:1] op_sel_hi:[1,0]
	v_pk_mul_f32 v[16:17], v[16:17], v[0:1] op_sel_hi:[1,0]
	v_pk_mul_f32 v[14:15], v[14:15], v[0:1] op_sel_hi:[1,0]
	v_pk_mul_f32 v[20:21], v[20:21], v[0:1] op_sel_hi:[1,0]
	v_pk_mul_f32 v[18:19], v[18:19], v[0:1] op_sel_hi:[1,0]
	v_pk_mul_f32 v[12:13], v[12:13], v[0:1] op_sel_hi:[1,0]
	v_pk_mul_f32 v[10:11], v[10:11], v[0:1] op_sel_hi:[1,0]
	v_pk_mul_f32 v[8:9], v[8:9], v[0:1] op_sel_hi:[1,0]
	v_pk_mul_f32 v[6:7], v[6:7], v[0:1] op_sel_hi:[1,0]
	v_pk_mul_f32 v[4:5], v[4:5], v[0:1] op_sel_hi:[1,0]
	v_pk_mul_f32 v[2:3], v[2:3], v[0:1] op_sel_hi:[1,0]

; __device__ __forceinline__ float xor16_max(float v) { const auto r = __builtin_amdgcn_permlane16_swap(__float_as_uint(v), __float_as_uint(v), false, false); return fmaxf(__uint_as_float(r[0]), __uint_as_float(r[1])); }
; __device__ __forceinline__ void attn_phase(LAS unsigned char* lds, const bf16* PROJ, bf16* MIX, const float* lq1, const float* lk1, const float* lq2, const float* lk2,
;                                            const float* norm_g, float lambda_init, int G, int wave_s) {
;     ...
;                 { bf16x8 kfa[4], kfb[4];
;                   ATT_LDK(kfa, 0); ATT_LDK(kfb, 1); ATT_SB(); ATT_QK(kfa, 0); ATT_LDK(kfa, 2); ATT_SB(); ATT_QK(kfb, 1); ATT_LDK(kfb, 3); ATT_SB(); ATT_QK(kfa, 2); ATT_QK(kfb, 3); }
;                 const int dq = 64 * kt + qloc; const bool diag = (kt == 0);
;                 const float nb = -sl2 * ((float)dq - q4f);
;                 float mx = -1e30f;
; #pragma unroll
;                 for (int t16 = 0; t16 < 4; ++t16)
; #pragma unroll
;                     for (int r = 0; r < 4; ++r) { const int kl = 16 * t16 + 4 * q4 + r; float v = fmaf(s[t16][r], c1, fmaf(sl2, (float)(16 * t16 + r), nb));
;                         if (diag && kl > qloc) v = -1e30f; s[t16][r] = v; mx = fmaxf(mx, v); }
;                 mx = xor32_max(xor16_max(mx));
;                 const bool resc = __builtin_amdgcn_ballot_w64(mx > m_run) != 0ull;
;                 const float mn = fmaxf(m_run, mx), alpha = __builtin_amdgcn_exp2f(m_run - mn); m_run = mn;
;                 float ps = 0.f;
; #pragma unroll
;                 for (int t16 = 0; t16 < 4; ++t16)
; #pragma unroll
;                     for (int r = 0; r < 4; ++r) { const float pv = __builtin_amdgcn_exp2f(s[t16][r] - mn); s[t16][r] = pv; ps += pv; }
;                 l_part = l_part * alpha + ps;
;                 bf16x8 pf[2];
; #pragma unroll
;                 for (int ks = 0; ks < 2; ++ks) { v4u pw; pw.x = pk2(s[2 * ks][0], s[2 * ks][1]); pw.y = pk2(s[2 * ks][2], s[2 * ks][3]); pw.z = pk2(s[2 * ks + 1][0], s[2 * ks + 1][1]); pw.w = pk2(s[2 * ks + 1][2], s[2 * ks + 1][3]);
;                     pf[ks] = __builtin_bit_cast(bf16x8, pw); }
;                 { bf16x8 va[2], vb[2], vc[2];
;                   ATT_LDV(va, 0); ATT_LDV(vb, 1);
;                   if (resc) {
; #pragma unroll
;                   for (int mt = 0; mt < 16; ++mt) O[mt] = O[mt] * alpha; }
.LBB0_898:
	ds_read_b128 v[114:117], v210
	ds_read_b128 v[118:121], v210 offset:64
	ds_read_b128 v[122:125], v210 offset:128
	ds_read_b128 v[126:129], v210 offset:192
	ds_read_b128 v[130:133], v210 offset:4352
	ds_read_b128 v[134:137], v210 offset:4416
	ds_read_b128 v[230:233], v210 offset:4480
	ds_read_b128 v[234:237], v210 offset:4544
	s_waitcnt lgkmcnt(7)
	v_mfma_f32_16x16x32_bf16 v[114:117], v[114:117], v[74:77], 0
	s_waitcnt lgkmcnt(6)
	v_mfma_f32_16x16x32_bf16 v[114:117], v[118:121], v[66:69], v[114:117]
	s_waitcnt lgkmcnt(5)
	v_mfma_f32_16x16x32_bf16 v[114:117], v[122:125], v[70:73], v[114:117]
	s_waitcnt lgkmcnt(4)
	v_mfma_f32_16x16x32_bf16 v[116:119], v[126:129], v[78:81], v[114:117]
	ds_read_b128 v[120:123], v210 offset:8704
	ds_read_b128 v[124:127], v210 offset:8768
	ds_read_b128 v[238:241], v210 offset:8832
	ds_read_b128 v[242:245], v210 offset:8896
	s_waitcnt lgkmcnt(7)
	v_mfma_f32_16x16x32_bf16 v[128:131], v[130:133], v[74:77], 0
	s_waitcnt lgkmcnt(6)
	v_mfma_f32_16x16x32_bf16 v[128:131], v[134:137], v[66:69], v[128:131]
	s_waitcnt lgkmcnt(5)
	v_mfma_f32_16x16x32_bf16 v[128:131], v[230:233], v[70:73], v[128:131]
	s_waitcnt lgkmcnt(4)
	v_mfma_f32_16x16x32_bf16 v[128:131], v[234:237], v[78:81], v[128:131]
	ds_read_b128 v[132:135], v210 offset:13056
	ds_read_b128 v[230:233], v210 offset:13120
	ds_read_b128 v[234:237], v210 offset:13184
	ds_read_b128 v[246:249], v210 offset:13248
	s_waitcnt lgkmcnt(7)
	v_mfma_f32_16x16x32_bf16 v[120:123], v[120:123], v[74:77], 0
	v_add_u32_e32 v0, 64, v224
	v_cvt_f32_u32_e32 v0, v0
	v_sub_f32_e32 v0, v0, v166
	s_waitcnt lgkmcnt(3)
	v_mfma_f32_16x16x32_bf16 v[132:135], v[132:135], v[74:77], 0
	v_mul_f32_e64 v114, v0, -v211
	v_fma_f32 v115, 0, v211, v114
	v_fmac_f32_e32 v115, 0x3e0293ee, v116
	v_mfma_f32_16x16x32_bf16 v[120:123], v[124:127], v[66:69], v[120:123]
	v_fma_f32 v116, v0, -v211, v211
	v_fmac_f32_e32 v116, 0x3e0293ee, v117
	v_fma_f32 v117, 2.0, v211, v114
	s_waitcnt lgkmcnt(2)
	v_mfma_f32_16x16x32_bf16 v[132:135], v[230:233], v[66:69], v[132:135]
	v_fmac_f32_e32 v117, 0x3e0293ee, v118
	v_fmamk_f32 v118, v211, 0x40400000, v114
	v_max3_f32 v0, v115, s4, v116
	v_mfma_f32_16x16x32_bf16 v[120:123], v[238:241], v[70:73], v[120:123]
	v_fmac_f32_e32 v118, 0x3e0293ee, v119
	v_fmamk_f32 v119, v211, 0x41800000, v114
	v_max3_f32 v0, v0, v117, v118
	s_waitcnt lgkmcnt(1)
	v_mfma_f32_16x16x32_bf16 v[132:135], v[234:237], v[70:73], v[132:135]
	v_fmac_f32_e32 v119, 0x3e0293ee, v128
	v_fmamk_f32 v225, v211, 0x41980000, v114
	v_fmac_f32_e32 v225, 0x3e0293ee, v131
	v_mfma_f32_16x16x32_bf16 v[122:125], v[242:245], v[78:81], v[120:123]
	v_fmamk_f32 v230, v211, 0x42000000, v114
	v_fmamk_f32 v231, v211, 0x42040000, v114
	v_fmamk_f32 v233, v211, 0x42080000, v114
	v_fmamk_f32 v120, v211, 0x41880000, v114
	s_waitcnt lgkmcnt(0)
	v_mfma_f32_16x16x32_bf16 v[132:135], v[246:249], v[78:81], v[132:135]
	v_fmac_f32_e32 v120, 0x3e0293ee, v129
	v_fmamk_f32 v121, v211, 0x41900000, v114
	v_max3_f32 v0, v0, v119, v120
	v_fmac_f32_e32 v121, 0x3e0293ee, v130
	v_max3_f32 v0, v0, v121, v225
	v_fmac_f32_e32 v230, 0x3e0293ee, v122
	v_fmac_f32_e32 v231, 0x3e0293ee, v123
	v_fmamk_f32 v234, v211, 0x420c0000, v114
	v_max3_f32 v0, v0, v230, v231
	v_fmac_f32_e32 v233, 0x3e0293ee, v124
	v_fmac_f32_e32 v234, 0x3e0293ee, v125
	v_fmamk_f32 v229, v211, 0x42400000, v114
	v_fmamk_f32 v232, v211, 0x42440000, v114
	v_max3_f32 v0, v0, v233, v234
	v_fmac_f32_e32 v229, 0x3e0293ee, v132
	v_fmac_f32_e32 v232, 0x3e0293ee, v133
	v_fmamk_f32 v235, v211, 0x42480000, v114
	v_fmac_f32_e32 v114, 0x424c0000, v211
	v_max3_f32 v0, v0, v229, v232
	v_fmac_f32_e32 v235, 0x3e0293ee, v134
	v_fmac_f32_e32 v114, 0x3e0293ee, v135
	v_max3_f32 v0, v0, v235, v114
	v_mov_b32_e32 v122, v0
	s_nop 1
	v_permlane16_swap_b32_e32 v0, v122
	v_max_f32_e32 v0, v0, v122
	v_mov_b32_e32 v122, v0
	s_nop 1
	v_permlane32_swap_b32_e32 v0, v122
	v_max_f32_e32 v0, v0, v122
	v_max_f32_e32 v226, v228, v0
	v_add_u32_e32 v122, 0x19800, v162
	v_add_u32_e32 v124, 0x1fe20, v162
	ds_read_b64_tr_b16 v[134:135], v122
	ds_read_b64_tr_b16 v[124:125], v124
	v_add_u32_e32 v122, 0x1ba00, v162
	ds_read_b64_tr_b16 v[136:137], v122
	v_add_u32_e32 v122, 0x1dc00, v162
	ds_read_b64_tr_b16 v[126:127], v122
	v_add_u32_e32 v122, 0x1fe00, v162
	ds_read_b64_tr_b16 v[128:129], v122
	v_add_u32_e32 v122, 0x19820, v162
	ds_read_b64_tr_b16 v[130:131], v122
	v_add_u32_e32 v122, 0x1ba20, v162
	ds_read_b64_tr_b16 v[132:133], v122
	v_add_u32_e32 v122, 0x1dc20, v162
	v_cmp_gt_f32_e32 vcc, v0, v228
	v_sub_f32_e32 v0, v228, v226
	ds_read_b64_tr_b16 v[122:123], v122
	v_exp_f32_e32 v0, v0
	s_cbranch_vccz .LBB0_900
	v_pk_mul_f32 v[64:65], v[64:65], v[0:1] op_sel_hi:[1,0]
	v_pk_mul_f32 v[62:63], v[62:63], v[0:1] op_sel_hi:[1,0]
	v_pk_mul_f32 v[60:61], v[60:61], v[0:1] op_sel_hi:[1,0]
	v_pk_mul_f32 v[58:59], v[58:59], v[0:1] op_sel_hi:[1,0]
	v_pk_mul_f32 v[56:57], v[56:57], v[0:1] op_sel_hi:[1,0]
	v_pk_mul_f32 v[54:55], v[54:55], v[0:1] op_sel_hi:[1,0]
	v_pk_mul_f32 v[52:53], v[52:53], v[0:1] op_sel_hi:[1,0]
	v_pk_mul_f32 v[50:51], v[50:51], v[0:1] op_sel_hi:[1,0]
	v_pk_mul_f32 v[48:49], v[48:49], v[0:1] op_sel_hi:[1,0]
	v_pk_mul_f32 v[46:47], v[46:47], v[0:1] op_sel_hi:[1,0]
	v_pk_mul_f32 v[44:45], v[44:45], v[0:1] op_sel_hi:[1,0]
	v_pk_mul_f32 v[42:43], v[42:43], v[0:1] op_sel_hi:[1,0]
	v_pk_mul_f32 v[40:41], v[40:41], v[0:1] op_sel_hi:[1,0]
	v_pk_mul_f32 v[38:39], v[38:39], v[0:1] op_sel_hi:[1,0]
	v_pk_mul_f32 v[36:37], v[36:37], v[0:1] op_sel_hi:[1,0]
	v_pk_mul_f32 v[34:35], v[34:35], v[0:1] op_sel_hi:[1,0]
	v_pk_mul_f32 v[32:33], v[32:33], v[0:1] op_sel_hi:[1,0]
	v_pk_mul_f32 v[30:31], v[30:31], v[0:1] op_sel_hi:[1,0]
	v_pk_mul_f32 v[28:29], v[28:29], v[0:1] op_sel_hi:[1,0]
	v_pk_mul_f32 v[26:27], v[26:27], v[0:1] op_sel_hi:[1,0]
	v_pk_mul_f32 v[24:25], v[24:25], v[0:1] op_sel_hi:[1,0]
	v_pk_mul_f32 v[22:23], v[22:23], v[0:1] op_sel_hi:[1,0]
	v_pk_mul_f32 v[16:17], v[16:17], v[0:1] op_sel_hi:[1,0]
	v_pk_mul_f32 v[14:15], v[14:15], v[0:1] op_sel_hi:[1,0]
	v_pk_mul_f32 v[20:21], v[20:21], v[0:1] op_sel_hi:[1,0]
	v_pk_mul_f32 v[18:19], v[18:19], v[0:1] op_sel_hi:[1,0]
	v_pk_mul_f32 v[12:13], v[12:13], v[0:1] op_sel_hi:[1,0]
	v_pk_mul_f32 v[10:11], v[10:11], v[0:1] op_sel_hi:[1,0]
	v_pk_mul_f32 v[8:9], v[8:9], v[0:1] op_sel_hi:[1,0]
	v_pk_mul_f32 v[6:7], v[6:7], v[0:1] op_sel_hi:[1,0]
	v_pk_mul_f32 v[4:5], v[4:5], v[0:1] op_sel_hi:[1,0]
	v_pk_mul_f32 v[2:3], v[2:3], v[0:1] op_sel_hi:[1,0]
